# as best + nt (streaming) cache policy on P1 x-row loads, keeps H/weights cached for the in-projection GEMM
# speedup vs baseline: 1.0248x; 1.0248x over previous
; __device__ __forceinline__ unsigned pk2(float lo, float hi) { unsigned r; asm("v_cvt_pk_bf16_f32 %0, %1, %2" : "=v"(r) : "v"(lo), "v"(hi)); return r; }
; __device__ __forceinline__ void p1_phase(const float* xin, const float* g, const float* modl, bf16* H, int wid, int lane) {
;     ...
;         for (int r = 0; r < 32; ++r) {
;             const float* xr = xin + (size_t)(base + r) * DM + 4 * lane;
;             f32x4 v[4]; float s = 0.f;
; #pragma unroll
;             for (int j = 0; j < 4; ++j) { v[j] = *(const f32x4*)(xr + 256 * j); s += (v[j][0] * v[j][0] + v[j][1] * v[j][1]) + (v[j][2] * v[j][2] + v[j][3] * v[j][3]); }
;             const float rs = __builtin_amdgcn_rsqf(wave_sum(s) * (1.0f / DM) + EPSN);
;             bf16* orow = H + (size_t)(base + r) * DM + 4 * lane;
; #pragma unroll
;             for (int j = 0; j < 4; ++j) { const f32x4 o = v[j] * rs * gs[j] + sh[j]; v2u w; w.x = pk2(o[0], o[1]); w.y = pk2(o[2], o[3]); *(v2u*)(orow + 256 * j) = w; }
;         }
.LBB0_82:
	v_lshl_add_u64 v[68:69], v[18:19], 0, s[12:13]
	global_load_dwordx4 v[52:55], v[68:69], off nt
	global_load_dwordx4 v[56:59], v[68:69], off offset:1024 nt
	global_load_dwordx4 v[60:63], v[68:69], off offset:2048 nt
	global_load_dwordx4 v[64:67], v[68:69], off offset:3072 nt
	s_add_u32 s12, s12, 0x1000
	s_addc_u32 s13, s13, 0
	s_cmp_eq_u32 s12, 0x20000
	s_waitcnt vmcnt(3)
	v_pk_mul_f32 v[68:69], v[54:55], v[54:55]
	v_pk_mul_f32 v[70:71], v[52:53], v[52:53]
	s_waitcnt vmcnt(2)
	v_pk_mul_f32 v[72:73], v[58:59], v[58:59]
	v_pk_mul_f32 v[74:75], v[56:57], v[56:57]
	v_pk_mov_b32 v[80:81], v[70:71], v[68:69] op_sel:[1,0]
	v_mov_b32_e32 v71, v69
	v_pk_mov_b32 v[68:69], v[74:75], v[72:73] op_sel:[1,0]
	v_mov_b32_e32 v75, v73
	s_waitcnt vmcnt(0)
	v_mul_f32_e32 v79, v65, v65
	v_mul_f32_e32 v76, v61, v61
	v_mul_f32_e32 v78, v63, v63
	v_pk_add_f32 v[70:71], v[80:81], v[70:71]
	v_pk_add_f32 v[68:69], v[68:69], v[74:75]
	v_mul_f32_e32 v51, v64, v64
	v_mul_f32_e32 v82, v66, v66
	v_mul_f32_e32 v83, v67, v67
	v_pk_fma_f32 v[72:73], v[60:61], v[60:61], v[76:77] op_sel_hi:[1,1,0]
	v_pk_fma_f32 v[76:77], v[62:63], v[62:63], v[78:79] op_sel_hi:[1,1,0]
	v_pk_add_f32 v[70:71], v[70:71], v[70:71] op_sel:[0,1] op_sel_hi:[1,0]
	v_pk_add_f32 v[68:69], v[68:69], v[68:69] op_sel:[0,1] op_sel_hi:[1,0]
	v_mov_b32_e32 v73, v82
	v_mov_b32_e32 v77, v83
	v_mov_b32_e32 v71, v51
	v_mov_b32_e32 v69, v79
	v_pk_add_f32 v[72:73], v[72:73], v[76:77]
	v_pk_add_f32 v[68:69], v[70:71], v[68:69]
	s_nop 0
	v_pk_add_f32 v[68:69], v[68:69], v[72:73]
	s_nop 0
	v_add_f32_e32 v51, v68, v69
	ds_bpermute_b32 v68, v40, v51
	s_waitcnt lgkmcnt(0)
	v_add_f32_e32 v51, v51, v68
	ds_bpermute_b32 v68, v41, v51
	s_waitcnt lgkmcnt(0)
	v_add_f32_e32 v51, v51, v68
	ds_bpermute_b32 v68, v42, v51
	s_waitcnt lgkmcnt(0)
	v_add_f32_e32 v51, v51, v68
	ds_bpermute_b32 v68, v43, v51
	s_waitcnt lgkmcnt(0)
	v_add_f32_e32 v51, v51, v68
	ds_bpermute_b32 v68, v44, v51
	s_waitcnt lgkmcnt(0)
	v_add_f32_e32 v51, v51, v68
	ds_bpermute_b32 v68, v45, v51
	s_waitcnt lgkmcnt(0)
	v_add_f32_e32 v51, v51, v68
	v_fmamk_f32 v51, v51, 0x3a800000, v50
	v_rsq_f32_e32 v68, v51
	s_nop 0
	v_pk_mul_f32 v[52:53], v[52:53], v[68:69] op_sel_hi:[1,0]
	v_pk_mul_f32 v[54:55], v[54:55], v[68:69] op_sel_hi:[1,0]
	v_pk_mul_f32 v[56:57], v[56:57], v[68:69] op_sel_hi:[1,0]
	v_pk_mul_f32 v[58:59], v[58:59], v[68:69] op_sel_hi:[1,0]
	v_pk_fma_f32 v[52:53], v[24:25], v[52:53], v[0:1]
	v_pk_mul_f32 v[60:61], v[60:61], v[68:69] op_sel_hi:[1,0]
	v_pk_mul_f32 v[62:63], v[62:63], v[68:69] op_sel_hi:[1,0]
	v_pk_mul_f32 v[64:65], v[64:65], v[68:69] op_sel_hi:[1,0]
	v_pk_mul_f32 v[66:67], v[66:67], v[68:69] op_sel_hi:[1,0]
	v_pk_fma_f32 v[54:55], v[22:23], v[54:55], v[2:3]
	v_pk_fma_f32 v[58:59], v[26:27], v[58:59], v[6:7]
	v_pk_fma_f32 v[56:57], v[28:29], v[56:57], v[4:5]
	v_cvt_pk_bf16_f32 v52, v52, v53
	v_cvt_pk_bf16_f32 v53, v54, v55
	v_pk_fma_f32 v[62:63], v[30:31], v[62:63], v[10:11]
	v_pk_fma_f32 v[60:61], v[32:33], v[60:61], v[8:9]
	v_pk_fma_f32 v[66:67], v[34:35], v[66:67], v[14:15]
	v_pk_fma_f32 v[64:65], v[36:37], v[64:65], v[12:13]
	v_cvt_pk_bf16_f32 v54, v56, v57
	v_cvt_pk_bf16_f32 v55, v58, v59
	v_cvt_pk_bf16_f32 v56, v60, v61
	v_cvt_pk_bf16_f32 v57, v62, v63
	v_cvt_pk_bf16_f32 v59, v66, v67
	s_nop 0
	v_cvt_pk_bf16_f32 v58, v64, v65
	global_store_dwordx2 v[38:39], v[52:53], off offset:-1024
	global_store_dwordx2 v[38:39], v[54:55], off offset:-512
	global_store_dwordx2 v[38:39], v[56:57], off
	global_store_dwordx2 v[38:39], v[58:59], off offset:512
	v_lshl_add_u64 v[38:39], v[38:39], 0, s[10:11]
	s_cbranch_scc0 .LBB0_82
	s_add_i32 s0, s0, s4
	v_lshl_add_u64 v[18:19], v[18:19], 0, s[6:7]
	s_cmp_gt_i32 s0, 0xffff
	v_lshl_add_u64 v[20:21], v[20:21], 0, s[8:9]
	s_cbranch_scc0 .LBB0_81

; __device__ __forceinline__ unsigned pk2(float lo, float hi) { unsigned r; asm("v_cvt_pk_bf16_f32 %0, %1, %2" : "=v"(r) : "v"(lo), "v"(hi)); return r; }
; __device__ __forceinline__ void p1_phase(const float* xin, const float* g, const float* modl, bf16* H, int wid, int lane) {
;     ...
;         for (int r = 0; r < 32; ++r) {
;             const float* xr = xin + (size_t)(base + r) * DM + 4 * lane;
;             f32x4 v[4]; float s = 0.f;
; #pragma unroll
;             for (int j = 0; j < 4; ++j) { v[j] = *(const f32x4*)(xr + 256 * j); s += (v[j][0] * v[j][0] + v[j][1] * v[j][1]) + (v[j][2] * v[j][2] + v[j][3] * v[j][3]); }
;             const float rs = __builtin_amdgcn_rsqf(wave_sum(s) * (1.0f / DM) + EPSN);
;             bf16* orow = H + (size_t)(base + r) * DM + 4 * lane;
; #pragma unroll
;             for (int j = 0; j < 4; ++j) { const f32x4 o = v[j] * rs * gs[j] + sh[j]; v2u w; w.x = pk2(o[0], o[1]); w.y = pk2(o[2], o[3]); *(v2u*)(orow + 256 * j) = w; }
;         }
.LBB0_607:
	v_lshl_add_u64 v[74:75], v[24:25], 0, s[12:13]
	global_load_dwordx4 v[58:61], v[74:75], off nt
	global_load_dwordx4 v[62:65], v[74:75], off offset:1024 nt
	global_load_dwordx4 v[66:69], v[74:75], off offset:2048 nt
	global_load_dwordx4 v[70:73], v[74:75], off offset:3072 nt
	s_add_u32 s12, s12, 0x1000
	s_addc_u32 s13, s13, 0
	s_cmp_eq_u32 s12, 0x20000
	s_waitcnt vmcnt(3)
	v_pk_mul_f32 v[74:75], v[60:61], v[60:61]
	v_pk_mul_f32 v[76:77], v[58:59], v[58:59]
	s_waitcnt vmcnt(2)
	v_pk_mul_f32 v[78:79], v[64:65], v[64:65]
	v_pk_mul_f32 v[80:81], v[62:63], v[62:63]
	v_pk_mov_b32 v[86:87], v[76:77], v[74:75] op_sel:[1,0]
	v_mov_b32_e32 v77, v75
	v_pk_mov_b32 v[74:75], v[80:81], v[78:79] op_sel:[1,0]
	v_mov_b32_e32 v81, v79
	s_waitcnt vmcnt(0)
	v_mul_f32_e32 v85, v71, v71
	v_mul_f32_e32 v82, v67, v67
	v_mul_f32_e32 v84, v69, v69
	v_pk_add_f32 v[76:77], v[86:87], v[76:77]
	v_pk_add_f32 v[74:75], v[74:75], v[80:81]
	v_mul_f32_e32 v57, v70, v70
	v_mul_f32_e32 v88, v72, v72
	v_mul_f32_e32 v89, v73, v73
	v_pk_fma_f32 v[78:79], v[66:67], v[66:67], v[82:83] op_sel_hi:[1,1,0]
	v_pk_fma_f32 v[82:83], v[68:69], v[68:69], v[84:85] op_sel_hi:[1,1,0]
	v_pk_add_f32 v[76:77], v[76:77], v[76:77] op_sel:[0,1] op_sel_hi:[1,0]
	v_pk_add_f32 v[74:75], v[74:75], v[74:75] op_sel:[0,1] op_sel_hi:[1,0]
	v_mov_b32_e32 v79, v88
	v_mov_b32_e32 v83, v89
	v_mov_b32_e32 v77, v57
	v_mov_b32_e32 v75, v85
	v_pk_add_f32 v[78:79], v[78:79], v[82:83]
	v_pk_add_f32 v[74:75], v[76:77], v[74:75]
	s_nop 0
	v_pk_add_f32 v[74:75], v[74:75], v[78:79]
	s_nop 0
	v_add_f32_e32 v57, v74, v75
	ds_bpermute_b32 v74, v46, v57
	s_waitcnt lgkmcnt(0)
	v_add_f32_e32 v57, v57, v74
	ds_bpermute_b32 v74, v47, v57
	s_waitcnt lgkmcnt(0)
	v_add_f32_e32 v57, v57, v74
	ds_bpermute_b32 v74, v48, v57
	s_waitcnt lgkmcnt(0)
	v_add_f32_e32 v57, v57, v74
	ds_bpermute_b32 v74, v49, v57
	s_waitcnt lgkmcnt(0)
	v_add_f32_e32 v57, v57, v74
	ds_bpermute_b32 v74, v50, v57
	s_waitcnt lgkmcnt(0)
	v_add_f32_e32 v57, v57, v74
	ds_bpermute_b32 v74, v51, v57
	s_waitcnt lgkmcnt(0)
	v_add_f32_e32 v57, v57, v74
	v_fmamk_f32 v57, v57, 0x3a800000, v56
	v_rsq_f32_e32 v74, v57
	s_nop 0
	v_pk_mul_f32 v[58:59], v[58:59], v[74:75] op_sel_hi:[1,0]
	v_pk_mul_f32 v[60:61], v[60:61], v[74:75] op_sel_hi:[1,0]
	v_pk_mul_f32 v[62:63], v[62:63], v[74:75] op_sel_hi:[1,0]
	v_pk_mul_f32 v[64:65], v[64:65], v[74:75] op_sel_hi:[1,0]
	v_pk_fma_f32 v[58:59], v[30:31], v[58:59], v[0:1]
	v_pk_mul_f32 v[66:67], v[66:67], v[74:75] op_sel_hi:[1,0]
	v_pk_mul_f32 v[68:69], v[68:69], v[74:75] op_sel_hi:[1,0]
	v_pk_mul_f32 v[70:71], v[70:71], v[74:75] op_sel_hi:[1,0]
	v_pk_mul_f32 v[72:73], v[72:73], v[74:75] op_sel_hi:[1,0]
	v_pk_fma_f32 v[60:61], v[28:29], v[60:61], v[2:3]
	v_pk_fma_f32 v[64:65], v[32:33], v[64:65], v[6:7]
	v_pk_fma_f32 v[62:63], v[34:35], v[62:63], v[4:5]
	v_cvt_pk_bf16_f32 v58, v58, v59
	v_cvt_pk_bf16_f32 v59, v60, v61
	v_pk_fma_f32 v[68:69], v[36:37], v[68:69], v[10:11]
	v_pk_fma_f32 v[66:67], v[38:39], v[66:67], v[8:9]
	v_pk_fma_f32 v[72:73], v[40:41], v[72:73], v[14:15]
	v_pk_fma_f32 v[70:71], v[42:43], v[70:71], v[12:13]
	v_cvt_pk_bf16_f32 v60, v62, v63
	v_cvt_pk_bf16_f32 v61, v64, v65
	v_cvt_pk_bf16_f32 v62, v66, v67
	v_cvt_pk_bf16_f32 v63, v68, v69
	v_cvt_pk_bf16_f32 v65, v72, v73
	s_nop 0
	v_cvt_pk_bf16_f32 v64, v70, v71
	global_store_dwordx2 v[44:45], v[58:59], off offset:-1024
	global_store_dwordx2 v[44:45], v[60:61], off offset:-512
	global_store_dwordx2 v[44:45], v[62:63], off
	global_store_dwordx2 v[44:45], v[64:65], off offset:512
	v_lshl_add_u64 v[44:45], v[44:45], 0, s[10:11]
	s_cbranch_scc0 .LBB0_607
	s_add_i32 s0, s0, s8
	v_lshl_add_u64 v[24:25], v[24:25], 0, s[4:5]
	s_cmp_gt_i32 s0, 0xffff
	v_lshl_add_u64 v[26:27], v[26:27], 0, s[6:7]
	s_cbranch_scc0 .LBB0_606
